# attention epilogue: sub-LN gain loads for 10 of 13 steps issued up front (v96-135), counted vmcnt instead of load/vmcnt(0)/store ladder; on top of v35 stack
# baseline (speedup 1.0000x reference)
; __device__ __forceinline__ void attn_item(PC p, int wv, int L, int item, LAS unsigned char* lds) {
;     ...
;         lam = __expf(s1) - __expf(s2) + lam_init;
;     ...
;     if (m == 0) {
;         float ssq = 0.f;
; #pragma unroll
;         for (int dvt = 0; dvt < 4; ++dvt)
; #pragma unroll
;             for (int r = 0; r < 16; ++r) { const int dv = 32 * dvt + (r >> 2) * 8 + 4 * g + (r & 3); const float o = O[dvt][r] * inv - lam * Oex[(qs * 128 + dv) * 32 + j]; O[dvt][r] = o; ssq += o * o; }
.LBB0_367:
	s_and_b64 vcc, exec, s[4:5]
	s_waitcnt lgkmcnt(0)
	s_barrier
	s_cbranch_vccnz .LBB0_369
	v_add_f32_e32 v65, v184, v186
	v_add_f32_e32 v66, v185, v187
	v_mul_f32_e32 v65, 0x3fb8aa3b, v65
	v_mul_f32_e32 v66, 0x3fb8aa3b, v66
	v_exp_f32_e32 v65, v65
	v_exp_f32_e32 v66, v66
	v_readlane_b32 s4, v246, 10
	v_lshlrev_b32_e32 v136, 12, v143
	s_lshl_b32 s54, s16, 1
	v_sub_f32_e32 v65, v65, v66
	v_add_f32_e32 v66, 0x3e4ccccc, v65
	v_lshl_add_u32 v65, v183, 2, s4
	v_lshl_add_u32 v67, v188, 9, v65
	v_add_u32_e32 v68, 0x400, v67
	ds_read2_b32 v[74:75], v67 offset1:32
	ds_read2_b32 v[70:71], v67 offset0:64 offset1:96
	ds_read2_b32 v[84:85], v68 offset1:32
	ds_read2_b32 v[92:93], v68 offset0:64 offset1:96
	v_add_u32_e32 v68, 0x800, v67
	ds_read2_b32 v[108:109], v68 offset1:32
	ds_read2_b32 v[110:111], v68 offset0:64 offset1:96
	v_add_u32_e32 v68, 0xc00, v67
	ds_read2_b32 v[112:113], v68 offset1:32
	ds_read2_b32 v[114:115], v68 offset0:64 offset1:96
	v_add_u32_e32 v68, 0x1000, v67
	ds_read2_b32 v[116:117], v68 offset0:32 offset1:64
	v_add_u32_e32 v68, 0x1100, v67
	ds_read2_b32 v[118:119], v68 offset0:32 offset1:192
	v_add_u32_e32 v68, 0x1400, v67
	ds_read2_b32 v[120:121], v68 offset0:32 offset1:64
	v_add_u32_e32 v68, 0x1500, v67
	ds_read2_b32 v[122:123], v68 offset0:32 offset1:192
	v_add_u32_e32 v68, 0x1800, v67
	ds_read2_b32 v[124:125], v68 offset0:32 offset1:64
	v_add_u32_e32 v68, 0x1900, v67
	ds_read2_b32 v[126:127], v68 offset0:32 offset1:192
	v_add_u32_e32 v68, 0x1c00, v67
	ds_read2_b32 v[128:129], v68 offset0:32 offset1:64
	v_add_u32_e32 v68, 0x80, v67
	ds_read2st64_b32 v[130:131], v68 offset0:29 offset1:32
	v_add_u32_e32 v68, 0x2000, v67
	v_lshl_add_u32 v65, v141, 7, v65
	ds_read2_b32 v[132:133], v68 offset0:64 offset1:96
	v_add_u32_e32 v68, 0x2400, v67
	ds_read2st64_b32 v[96:97], v65 offset0:16 offset1:32
	ds_read2_b32 v[106:107], v68 offset1:32
	ds_read2_b32 v[134:135], v68 offset0:64 offset1:96
	v_add_u32_e32 v68, 0x2800, v67
	ds_read2_b32 v[100:101], v68 offset1:32
	ds_read2_b32 v[104:105], v68 offset0:64 offset1:96
	v_add_u32_e32 v68, 0x2c00, v67
	ds_read2_b32 v[94:95], v68 offset1:32
	ds_read2_b32 v[98:99], v68 offset0:64 offset1:96
	v_add_u32_e32 v68, 0x3000, v67
	ds_read2_b32 v[90:91], v68 offset0:32 offset1:64
	v_add_u32_e32 v68, 0x3100, v67
	ds_read2_b32 v[86:87], v68 offset0:32 offset1:192
	v_add_u32_e32 v68, 0x3400, v67
	ds_read2_b32 v[88:89], v68 offset0:32 offset1:64
	v_add_u32_e32 v68, 0x3500, v67
	ds_read2_b32 v[78:79], v68 offset0:32 offset1:192
	v_add_u32_e32 v68, 0x3800, v67
	ds_read2_b32 v[80:81], v68 offset0:32 offset1:64
	v_add_u32_e32 v68, 0x3900, v67
	ds_read2_b32 v[72:73], v68 offset0:32 offset1:192
	v_add_u32_e32 v68, 0x3c00, v67
	s_load_dwordx2 s[4:5], s[52:53], 0x48
	s_load_dwordx2 s[8:9], s[52:53], 0x110
	ds_read2_b32 v[76:77], v68 offset0:32 offset1:64
	ds_read_b32 v102, v65 offset:12288
	ds_read_b32 v83, v67 offset:15744
	v_lshlrev_b32_e32 v65, 2, v141
	s_waitcnt lgkmcnt(0)
	v_pk_mul_f32 v[70:71], v[66:67], v[70:71] op_sel_hi:[0,1]
	v_pk_fma_f32 v[70:71], v[50:51], v[64:65], v[70:71] op_sel_hi:[1,0,1] neg_lo:[0,0,1] neg_hi:[0,0,1]
	v_pk_mul_f32 v[50:51], v[66:67], v[74:75] op_sel_hi:[0,1]
	v_pk_fma_f32 v[74:75], v[48:49], v[64:65], v[50:51] op_sel_hi:[1,0,1] neg_lo:[0,0,1] neg_hi:[0,0,1]
	v_mul_f32_e32 v82, v71, v71
	v_mul_f32_e32 v48, v75, v75
	v_pk_fma_f32 v[142:143], v[74:75], v[74:75], v[48:49] op_sel_hi:[1,1,0]
	v_pk_mul_f32 v[84:85], v[66:67], v[84:85] op_sel_hi:[0,1]
	v_pk_fma_f32 v[142:143], v[70:71], v[70:71], v[142:143]
	v_pk_fma_f32 v[84:85], v[52:53], v[64:65], v[84:85] op_sel_hi:[1,0,1] neg_lo:[0,0,1] neg_hi:[0,0,1]
	v_pk_add_f32 v[142:143], v[142:143], v[82:83] op_sel_hi:[1,0]
	v_pk_mul_f32 v[92:93], v[66:67], v[92:93] op_sel_hi:[0,1]
	v_pk_fma_f32 v[52:53], v[84:85], v[84:85], v[142:143]
	v_mul_f32_e32 v82, v85, v85
	v_pk_fma_f32 v[54:55], v[54:55], v[64:65], v[92:93] op_sel_hi:[1,0,1] neg_lo:[0,0,1] neg_hi:[0,0,1]
	v_pk_add_f32 v[52:53], v[52:53], v[82:83] op_sel_hi:[1,0]
	v_mul_f32_e32 v82, v55, v55
	v_pk_fma_f32 v[52:53], v[54:55], v[54:55], v[52:53]
	global_load_dwordx4 v[48:51], v65, s[4:5]
	v_pk_add_f32 v[92:93], v[52:53], v[82:83] op_sel_hi:[1,0]
	v_pk_mul_f32 v[52:53], v[66:67], v[110:111] op_sel_hi:[0,1]
	v_pk_fma_f32 v[52:53], v[58:59], v[64:65], v[52:53] op_sel_hi:[1,0,1] neg_lo:[0,0,1] neg_hi:[0,0,1]
	v_pk_mul_f32 v[58:59], v[66:67], v[108:109] op_sel_hi:[0,1]
	v_pk_fma_f32 v[58:59], v[56:57], v[64:65], v[58:59] op_sel_hi:[1,0,1] neg_lo:[0,0,1] neg_hi:[0,0,1]
	v_mov_b32_e32 v103, v90
	v_pk_fma_f32 v[56:57], v[58:59], v[58:59], v[92:93]
	v_mul_f32_e32 v82, v59, v59
	v_pk_add_f32 v[56:57], v[56:57], v[82:83] op_sel_hi:[1,0]
	v_mul_f32_e32 v82, v53, v53
	v_pk_fma_f32 v[56:57], v[52:53], v[52:53], v[56:57]
	v_lshl_add_u64 v[68:69], s[8:9], 0, v[136:137]
	v_pk_add_f32 v[92:93], v[56:57], v[82:83] op_sel_hi:[1,0]
	v_pk_mul_f32 v[56:57], v[66:67], v[114:115] op_sel_hi:[0,1]
	v_pk_fma_f32 v[56:57], v[62:63], v[64:65], v[56:57] op_sel_hi:[1,0,1] neg_lo:[0,0,1] neg_hi:[0,0,1]
	v_pk_mul_f32 v[62:63], v[66:67], v[112:113] op_sel_hi:[0,1]
	v_pk_fma_f32 v[60:61], v[60:61], v[64:65], v[62:63] op_sel_hi:[1,0,1] neg_lo:[0,0,1] neg_hi:[0,0,1]
	v_lshlrev_b32_e32 v136, 1, v141
	v_pk_fma_f32 v[62:63], v[60:61], v[60:61], v[92:93]
	v_mul_f32_e32 v82, v61, v61
	v_pk_add_f32 v[62:63], v[62:63], v[82:83] op_sel_hi:[1,0]
	v_mul_f32_e32 v82, v57, v57
	v_pk_fma_f32 v[62:63], v[56:57], v[56:57], v[62:63]
	s_nop 0
	v_pk_add_f32 v[92:93], v[62:63], v[82:83] op_sel_hi:[1,0]
	v_mov_b32_e32 v62, v117
	v_mov_b32_e32 v63, v118
	v_pk_mul_f32 v[62:63], v[66:67], v[62:63] op_sel_hi:[0,1]
; __device__ __forceinline__ void attn_item(PC p, int wv, int L, int item, LAS unsigned char* lds) {
;     ...
;     if (m == 0) {
;         float ssq = 0.f;
; #pragma unroll
;         for (int dvt = 0; dvt < 4; ++dvt)
; #pragma unroll
;             for (int r = 0; r < 16; ++r) { const int dv = 32 * dvt + (r >> 2) * 8 + 4 * g + (r & 3); const float o = O[dvt][r] * inv - lam * Oex[(qs * 128 + dv) * 32 + j]; O[dvt][r] = o; ssq += o * o; }
	v_pk_fma_f32 v[34:35], v[34:35], v[64:65], v[62:63] op_sel_hi:[1,0,1] neg_lo:[0,0,1] neg_hi:[0,0,1]
	v_mov_b32_e32 v62, v96
	v_mov_b32_e32 v63, v116
	v_pk_mul_f32 v[62:63], v[66:67], v[62:63] op_sel_hi:[0,1]
	v_pk_fma_f32 v[62:63], v[32:33], v[64:65], v[62:63] op_sel_hi:[1,0,1] neg_lo:[0,0,1] neg_hi:[0,0,1]
	s_nop 0
	v_pk_fma_f32 v[32:33], v[62:63], v[62:63], v[92:93]
	v_mul_f32_e32 v82, v63, v63
	v_pk_add_f32 v[32:33], v[32:33], v[82:83] op_sel_hi:[1,0]
	v_mul_f32_e32 v82, v35, v35
	v_pk_fma_f32 v[32:33], v[34:35], v[34:35], v[32:33]
	s_nop 0
	v_pk_add_f32 v[108:109], v[32:33], v[82:83] op_sel_hi:[1,0]
	v_mov_b32_e32 v32, v121
	v_mov_b32_e32 v33, v122
	v_pk_mul_f32 v[32:33], v[66:67], v[32:33] op_sel_hi:[0,1]
	v_pk_fma_f32 v[32:33], v[38:39], v[64:65], v[32:33] op_sel_hi:[1,0,1] neg_lo:[0,0,1] neg_hi:[0,0,1]
	v_mov_b32_e32 v38, v119
	v_mov_b32_e32 v39, v120
	v_pk_mul_f32 v[38:39], v[66:67], v[38:39] op_sel_hi:[0,1]
	v_pk_fma_f32 v[92:93], v[36:37], v[64:65], v[38:39] op_sel_hi:[1,0,1] neg_lo:[0,0,1] neg_hi:[0,0,1]
	v_mov_b32_e32 v82, v77
	v_pk_fma_f32 v[36:37], v[92:93], v[92:93], v[108:109]
	v_mul_f32_e32 v38, v93, v93
	v_pk_add_f32 v[36:37], v[36:37], v[38:39] op_sel_hi:[1,0]
	v_mul_f32_e32 v38, v33, v33
	v_pk_fma_f32 v[36:37], v[32:33], v[32:33], v[36:37]
	s_nop 0
	v_pk_add_f32 v[38:39], v[36:37], v[38:39] op_sel_hi:[1,0]
	v_mov_b32_e32 v36, v125
	v_mov_b32_e32 v37, v126
	v_pk_mul_f32 v[36:37], v[66:67], v[36:37] op_sel_hi:[0,1]
	v_pk_fma_f32 v[36:37], v[42:43], v[64:65], v[36:37] op_sel_hi:[1,0,1] neg_lo:[0,0,1] neg_hi:[0,0,1]
	v_mov_b32_e32 v42, v123
	v_mov_b32_e32 v43, v124
	v_pk_mul_f32 v[42:43], v[66:67], v[42:43] op_sel_hi:[0,1]
	v_pk_fma_f32 v[40:41], v[40:41], v[64:65], v[42:43] op_sel_hi:[1,0,1] neg_lo:[0,0,1] neg_hi:[0,0,1]
	s_nop 0
	v_pk_fma_f32 v[38:39], v[40:41], v[40:41], v[38:39]
	v_mul_f32_e32 v42, v41, v41
	v_pk_add_f32 v[38:39], v[38:39], v[42:43] op_sel_hi:[1,0]
	v_mul_f32_e32 v42, v37, v37
	v_pk_fma_f32 v[38:39], v[36:37], v[36:37], v[38:39]
	s_nop 0
	v_pk_add_f32 v[108:109], v[38:39], v[42:43] op_sel_hi:[1,0]
	v_mov_b32_e32 v42, v127
	v_mov_b32_e32 v43, v128
	v_mov_b32_e32 v38, v129
	v_mov_b32_e32 v39, v130
	v_pk_mul_f32 v[42:43], v[66:67], v[42:43] op_sel_hi:[0,1]
	v_pk_mul_f32 v[38:39], v[66:67], v[38:39] op_sel_hi:[0,1]
	v_pk_fma_f32 v[42:43], v[44:45], v[64:65], v[42:43] op_sel_hi:[1,0,1] neg_lo:[0,0,1] neg_hi:[0,0,1]
	v_pk_fma_f32 v[38:39], v[46:47], v[64:65], v[38:39] op_sel_hi:[1,0,1] neg_lo:[0,0,1] neg_hi:[0,0,1]
	v_pk_fma_f32 v[44:45], v[42:43], v[42:43], v[108:109]
	v_mul_f32_e32 v46, v43, v43
	v_pk_add_f32 v[44:45], v[44:45], v[46:47] op_sel_hi:[1,0]
	v_mul_f32_e32 v46, v39, v39
	v_pk_fma_f32 v[44:45], v[38:39], v[38:39], v[44:45]
	v_mov_b32_e32 v130, v97
	v_pk_add_f32 v[46:47], v[44:45], v[46:47] op_sel_hi:[1,0]
	v_pk_mul_f32 v[44:45], v[66:67], v[132:133] op_sel_hi:[0,1]
	v_pk_fma_f32 v[18:19], v[18:19], v[64:65], v[44:45] op_sel_hi:[1,0,1] neg_lo:[0,0,1] neg_hi:[0,0,1]
	v_pk_mul_f32 v[44:45], v[66:67], v[130:131] op_sel_hi:[0,1]
	v_pk_fma_f32 v[44:45], v[16:17], v[64:65], v[44:45] op_sel_hi:[1,0,1] neg_lo:[0,0,1] neg_hi:[0,0,1]
	s_nop 0
	v_pk_fma_f32 v[16:17], v[44:45], v[44:45], v[46:47]
	v_mul_f32_e32 v46, v45, v45
	v_pk_add_f32 v[16:17], v[16:17], v[46:47] op_sel_hi:[1,0]
	v_mul_f32_e32 v46, v19, v19
	v_pk_fma_f32 v[16:17], v[18:19], v[18:19], v[16:17]
	s_nop 0
	v_pk_add_f32 v[96:97], v[16:17], v[46:47] op_sel_hi:[1,0]
	v_pk_mul_f32 v[16:17], v[66:67], v[134:135] op_sel_hi:[0,1]
	v_pk_fma_f32 v[16:17], v[22:23], v[64:65], v[16:17] op_sel_hi:[1,0,1] neg_lo:[0,0,1] neg_hi:[0,0,1]
	v_pk_mul_f32 v[22:23], v[66:67], v[106:107] op_sel_hi:[0,1]
	v_pk_fma_f32 v[46:47], v[20:21], v[64:65], v[22:23] op_sel_hi:[1,0,1] neg_lo:[0,0,1] neg_hi:[0,0,1]
	s_nop 0
	v_pk_fma_f32 v[20:21], v[46:47], v[46:47], v[96:97]
	v_mul_f32_e32 v22, v47, v47
	v_pk_add_f32 v[20:21], v[20:21], v[22:23] op_sel_hi:[1,0]
	v_mul_f32_e32 v22, v17, v17
	v_pk_fma_f32 v[20:21], v[16:17], v[16:17], v[20:21]
	s_nop 0
	v_pk_add_f32 v[22:23], v[20:21], v[22:23] op_sel_hi:[1,0]
	v_pk_mul_f32 v[20:21], v[66:67], v[104:105] op_sel_hi:[0,1]
	v_pk_fma_f32 v[20:21], v[26:27], v[64:65], v[20:21] op_sel_hi:[1,0,1] neg_lo:[0,0,1] neg_hi:[0,0,1]
	v_pk_mul_f32 v[26:27], v[66:67], v[100:101] op_sel_hi:[0,1]
	v_pk_fma_f32 v[24:25], v[24:25], v[64:65], v[26:27] op_sel_hi:[1,0,1] neg_lo:[0,0,1] neg_hi:[0,0,1]
	s_nop 0
	v_pk_fma_f32 v[22:23], v[24:25], v[24:25], v[22:23]
	v_mul_f32_e32 v26, v25, v25
	v_pk_add_f32 v[22:23], v[22:23], v[26:27] op_sel_hi:[1,0]
	v_mul_f32_e32 v26, v21, v21
	v_pk_fma_f32 v[22:23], v[20:21], v[20:21], v[22:23]
	s_nop 0
	v_pk_add_f32 v[96:97], v[22:23], v[26:27] op_sel_hi:[1,0]
	v_pk_mul_f32 v[26:27], v[66:67], v[94:95] op_sel_hi:[0,1]
	v_pk_mul_f32 v[22:23], v[66:67], v[98:99] op_sel_hi:[0,1]
	v_pk_fma_f32 v[26:27], v[28:29], v[64:65], v[26:27] op_sel_hi:[1,0,1] neg_lo:[0,0,1] neg_hi:[0,0,1]
	v_pk_fma_f32 v[22:23], v[30:31], v[64:65], v[22:23] op_sel_hi:[1,0,1] neg_lo:[0,0,1] neg_hi:[0,0,1]
	v_pk_fma_f32 v[28:29], v[26:27], v[26:27], v[96:97]
	v_mul_f32_e32 v30, v27, v27
	v_pk_add_f32 v[28:29], v[28:29], v[30:31] op_sel_hi:[1,0]
	v_mul_f32_e32 v30, v23, v23
	v_pk_fma_f32 v[28:29], v[22:23], v[22:23], v[28:29]
	s_nop 0
	v_pk_add_f32 v[30:31], v[28:29], v[30:31] op_sel_hi:[1,0]
	v_mov_b32_e32 v28, v91
	v_mov_b32_e32 v29, v86
	v_pk_mul_f32 v[28:29], v[66:67], v[28:29] op_sel_hi:[0,1]
	v_pk_fma_f32 v[2:3], v[2:3], v[64:65], v[28:29] op_sel_hi:[1,0,1] neg_lo:[0,0,1] neg_hi:[0,0,1]
	v_pk_mul_f32 v[28:29], v[66:67], v[102:103] op_sel_hi:[0,1]
	v_pk_fma_f32 v[28:29], v[0:1], v[64:65], v[28:29] op_sel_hi:[1,0,1] neg_lo:[0,0,1] neg_hi:[0,0,1]
; __device__ __forceinline__ void attn_item(PC p, int wv, int L, int item, LAS unsigned char* lds) {
;     ...
;             for (int r = 0; r < 16; ++r) { const int dv = 32 * dvt + (r >> 2) * 8 + 4 * g + (r & 3); const float o = O[dvt][r] * inv - lam * Oex[(qs * 128 + dv) * 32 + j]; O[dvt][r] = o; ssq += o * o; }
;         ssq = sum32(ssq);
;         const float sc = rsqrtf(ssq * (1.0f / 128.0f) + 1e-6f) * (1.0f - lam_init);
;         const float* sg = p->a_subln + L * 128;
;         u16* dst = p->mix + (tok0 + q0 + j) * DM + h * 128;
; #pragma unroll
;         for (int dvt = 0; dvt < 4; ++dvt)
; #pragma unroll
;             for (int r4 = 0; r4 < 4; ++r4) {
;                 const int dv = 32 * dvt + r4 * 8 + 4 * g;
;                 u32x2 o; o.x = pack2(O[dvt][4 * r4 + 0] * sc * sg[dv + 0], O[dvt][4 * r4 + 1] * sc * sg[dv + 1]);
;                 o.y = pack2(O[dvt][4 * r4 + 2] * sc * sg[dv + 2], O[dvt][4 * r4 + 3] * sc * sg[dv + 3]);
;                 *(u32x2*)(dst + dv) = o;
;             }
	s_nop 0
	v_pk_fma_f32 v[0:1], v[28:29], v[28:29], v[30:31]
	v_mul_f32_e32 v30, v29, v29
	v_pk_add_f32 v[0:1], v[0:1], v[30:31] op_sel_hi:[1,0]
	v_mul_f32_e32 v30, v3, v3
	v_pk_fma_f32 v[0:1], v[2:3], v[2:3], v[0:1]
	s_nop 0
	v_pk_add_f32 v[30:31], v[0:1], v[30:31] op_sel_hi:[1,0]
	v_mov_b32_e32 v0, v89
	v_mov_b32_e32 v1, v78
	v_pk_mul_f32 v[0:1], v[66:67], v[0:1] op_sel_hi:[0,1]
	v_pk_fma_f32 v[0:1], v[6:7], v[64:65], v[0:1] op_sel_hi:[1,0,1] neg_lo:[0,0,1] neg_hi:[0,0,1]
	v_mov_b32_e32 v6, v87
	v_mov_b32_e32 v7, v88
	v_pk_mul_f32 v[6:7], v[66:67], v[6:7] op_sel_hi:[0,1]
	v_pk_fma_f32 v[86:87], v[4:5], v[64:65], v[6:7] op_sel_hi:[1,0,1] neg_lo:[0,0,1] neg_hi:[0,0,1]
	s_nop 0
	v_pk_fma_f32 v[4:5], v[86:87], v[86:87], v[30:31]
	v_mul_f32_e32 v6, v87, v87
	v_pk_add_f32 v[4:5], v[4:5], v[6:7] op_sel_hi:[1,0]
	v_mul_f32_e32 v6, v1, v1
	v_pk_fma_f32 v[4:5], v[0:1], v[0:1], v[4:5]
	s_nop 0
	v_pk_add_f32 v[6:7], v[4:5], v[6:7] op_sel_hi:[1,0]
	v_mov_b32_e32 v4, v81
	v_mov_b32_e32 v5, v72
	v_pk_mul_f32 v[4:5], v[66:67], v[4:5] op_sel_hi:[0,1]
	v_pk_fma_f32 v[4:5], v[10:11], v[64:65], v[4:5] op_sel_hi:[1,0,1] neg_lo:[0,0,1] neg_hi:[0,0,1]
	v_mov_b32_e32 v10, v79
	v_mov_b32_e32 v11, v80
	v_pk_mul_f32 v[10:11], v[66:67], v[10:11] op_sel_hi:[0,1]
	v_pk_fma_f32 v[10:11], v[8:9], v[64:65], v[10:11] op_sel_hi:[1,0,1] neg_lo:[0,0,1] neg_hi:[0,0,1]
	s_nop 0
	v_pk_fma_f32 v[6:7], v[10:11], v[10:11], v[6:7]
	v_mul_f32_e32 v8, v11, v11
	v_pk_add_f32 v[6:7], v[6:7], v[8:9] op_sel_hi:[1,0]
	v_mul_f32_e32 v8, v5, v5
	v_pk_fma_f32 v[6:7], v[4:5], v[4:5], v[6:7]
	s_nop 0
	v_pk_add_f32 v[6:7], v[6:7], v[8:9] op_sel_hi:[1,0]
	v_pk_mul_f32 v[8:9], v[66:67], v[82:83] op_sel_hi:[0,1]
	v_pk_fma_f32 v[14:15], v[14:15], v[64:65], v[8:9] op_sel_hi:[1,0,1] neg_lo:[0,0,1] neg_hi:[0,0,1]
	v_mov_b32_e32 v8, v73
	v_mov_b32_e32 v9, v76
	v_pk_mul_f32 v[8:9], v[66:67], v[8:9] op_sel_hi:[0,1]
	v_pk_fma_f32 v[12:13], v[12:13], v[64:65], v[8:9] op_sel_hi:[1,0,1] neg_lo:[0,0,1] neg_hi:[0,0,1]
	s_nop 0
	v_pk_fma_f32 v[6:7], v[12:13], v[12:13], v[6:7]
	v_mul_f32_e32 v8, v13, v13
	v_pk_add_f32 v[6:7], v[6:7], v[8:9] op_sel_hi:[1,0]
	v_mul_f32_e32 v8, v15, v15
	v_pk_fma_f32 v[6:7], v[14:15], v[14:15], v[6:7]
	s_nop 0
	v_pk_add_f32 v[6:7], v[6:7], v[8:9] op_sel_hi:[1,0]
	s_nop 0
	v_mov_b32_e32 v7, v6
	s_nop 1
	v_permlane32_swap_b32_e32 v6, v7
	v_add_f32_e32 v6, v6, v7
	v_fmamk_f32 v6, v6, 0x3c000000, v153
	v_mul_f32_e32 v7, 0x4b800000, v6
	v_cmp_gt_f32_e32 vcc, s83, v6
	s_nop 1
	v_cndmask_b32_e32 v6, v6, v7, vcc
	v_rsq_f32_e32 v8, v6
	v_lshl_add_u64 v[6:7], v[68:69], 0, s[54:55]
	v_lshl_add_u64 v[30:31], v[6:7], 0, v[136:137]
	v_mul_f32_e32 v6, 0x45800000, v8
	v_cndmask_b32_e32 v6, v8, v6, vcc
	v_mul_f32_e32 v64, 0x3f4ccccd, v6
	v_pk_mul_f32 v[6:7], v[74:75], v[64:65] op_sel_hi:[1,0]
	v_pk_mul_f32 v[8:9], v[70:71], v[64:65] op_sel_hi:[1,0]
	s_waitcnt vmcnt(0)
	v_pk_mul_f32 v[6:7], v[48:49], v[6:7]
	v_pk_mul_f32 v[8:9], v[50:51], v[8:9]
	v_cvt_pk_bf16_f32 v6, v6, v7
	v_cvt_pk_bf16_f32 v7, v8, v9
	global_load_dwordx4 v[96:99], v65, s[4:5] offset:32
	global_load_dwordx4 v[100:103], v65, s[4:5] offset:64
	global_load_dwordx4 v[104:107], v65, s[4:5] offset:96
	global_load_dwordx4 v[108:111], v65, s[4:5] offset:128
	global_load_dwordx4 v[112:115], v65, s[4:5] offset:160
	global_load_dwordx4 v[116:119], v65, s[4:5] offset:192
	global_load_dwordx4 v[120:123], v65, s[4:5] offset:224
	global_load_dwordx4 v[124:127], v65, s[4:5] offset:256
	global_load_dwordx4 v[128:131], v65, s[4:5] offset:288
	global_load_dwordx4 v[132:135], v65, s[4:5] offset:320
	global_store_dwordx2 v[30:31], v[6:7], off
	v_pk_mul_f32 v[48:49], v[84:85], v[64:65] op_sel_hi:[1,0]
	v_pk_mul_f32 v[50:51], v[56:57], v[64:65] op_sel_hi:[1,0]
	v_pk_mul_f32 v[34:35], v[34:35], v[64:65] op_sel_hi:[1,0]
	v_pk_mul_f32 v[32:33], v[32:33], v[64:65] op_sel_hi:[1,0]
	v_pk_mul_f32 v[18:19], v[18:19], v[64:65] op_sel_hi:[1,0]
	v_pk_mul_f32 v[16:17], v[16:17], v[64:65] op_sel_hi:[1,0]
	v_pk_mul_f32 v[2:3], v[2:3], v[64:65] op_sel_hi:[1,0]
	v_pk_mul_f32 v[0:1], v[0:1], v[64:65] op_sel_hi:[1,0]
	v_pk_mul_f32 v[4:5], v[4:5], v[64:65] op_sel_hi:[1,0]
	s_waitcnt vmcnt(10)
	v_pk_mul_f32 v[6:7], v[96:97], v[48:49]
	v_pk_mul_f32 v[48:49], v[54:55], v[64:65] op_sel_hi:[1,0]
	v_cvt_pk_bf16_f32 v6, v6, v7
	v_pk_mul_f32 v[8:9], v[98:99], v[48:49]
	v_pk_mul_f32 v[48:49], v[58:59], v[64:65] op_sel_hi:[1,0]
	v_cvt_pk_bf16_f32 v7, v8, v9
	global_store_dwordx2 v[30:31], v[6:7], off offset:16
	s_waitcnt vmcnt(10)
; __device__ __forceinline__ void attn_item(PC p, int wv, int L, int item, LAS unsigned char* lds) {
;     ...
; #pragma unroll
;         for (int dvt = 0; dvt < 4; ++dvt)
; #pragma unroll
;             for (int r4 = 0; r4 < 4; ++r4) {
;                 const int dv = 32 * dvt + r4 * 8 + 4 * g;
;                 u32x2 o; o.x = pack2(O[dvt][4 * r4 + 0] * sc * sg[dv + 0], O[dvt][4 * r4 + 1] * sc * sg[dv + 1]);
;                 o.y = pack2(O[dvt][4 * r4 + 2] * sc * sg[dv + 2], O[dvt][4 * r4 + 3] * sc * sg[dv + 3]);
;                 *(u32x2*)(dst + dv) = o;
;             }
	v_pk_mul_f32 v[6:7], v[48:49], v[100:101]
	v_pk_mul_f32 v[48:49], v[52:53], v[64:65] op_sel_hi:[1,0]
	v_cvt_pk_bf16_f32 v6, v6, v7
	v_pk_mul_f32 v[8:9], v[48:49], v[102:103]
	v_pk_mul_f32 v[48:49], v[60:61], v[64:65] op_sel_hi:[1,0]
	v_cvt_pk_bf16_f32 v7, v8, v9
	global_store_dwordx2 v[30:31], v[6:7], off offset:32
	s_waitcnt vmcnt(10)
	v_pk_mul_f32 v[6:7], v[48:49], v[104:105]
	v_pk_mul_f32 v[8:9], v[50:51], v[106:107]
	v_cvt_pk_bf16_f32 v6, v6, v7
	v_cvt_pk_bf16_f32 v7, v8, v9
	global_store_dwordx2 v[30:31], v[6:7], off offset:48
	v_pk_mul_f32 v[48:49], v[62:63], v[64:65] op_sel_hi:[1,0]
	s_waitcnt vmcnt(10)
	v_pk_mul_f32 v[8:9], v[34:35], v[110:111]
	v_pk_mul_f32 v[6:7], v[48:49], v[108:109]
	v_pk_mul_f32 v[34:35], v[92:93], v[64:65] op_sel_hi:[1,0]
	v_cvt_pk_bf16_f32 v6, v6, v7
	v_cvt_pk_bf16_f32 v7, v8, v9
	global_store_dwordx2 v[30:31], v[6:7], off offset:64
	s_waitcnt vmcnt(10)
	v_pk_mul_f32 v[6:7], v[34:35], v[112:113]
	v_pk_mul_f32 v[8:9], v[32:33], v[114:115]
	v_cvt_pk_bf16_f32 v6, v6, v7
	v_cvt_pk_bf16_f32 v7, v8, v9
	global_store_dwordx2 v[30:31], v[6:7], off offset:80
	v_pk_mul_f32 v[32:33], v[40:41], v[64:65] op_sel_hi:[1,0]
	v_pk_mul_f32 v[34:35], v[36:37], v[64:65] op_sel_hi:[1,0]
	s_waitcnt vmcnt(10)
	v_pk_mul_f32 v[6:7], v[32:33], v[116:117]
	v_pk_mul_f32 v[8:9], v[34:35], v[118:119]
	v_cvt_pk_bf16_f32 v6, v6, v7
	v_cvt_pk_bf16_f32 v7, v8, v9
	global_store_dwordx2 v[30:31], v[6:7], off offset:96
	v_pk_mul_f32 v[32:33], v[42:43], v[64:65] op_sel_hi:[1,0]
	v_pk_mul_f32 v[34:35], v[38:39], v[64:65] op_sel_hi:[1,0]
	s_waitcnt vmcnt(10)
	v_pk_mul_f32 v[6:7], v[32:33], v[120:121]
	v_pk_mul_f32 v[8:9], v[34:35], v[122:123]
	v_cvt_pk_bf16_f32 v6, v6, v7
	v_cvt_pk_bf16_f32 v7, v8, v9
	global_store_dwordx2 v[30:31], v[6:7], off offset:112
	v_pk_mul_f32 v[32:33], v[44:45], v[64:65] op_sel_hi:[1,0]
	s_waitcnt vmcnt(10)
	v_pk_mul_f32 v[8:9], v[18:19], v[126:127]
	v_pk_mul_f32 v[6:7], v[32:33], v[124:125]
	v_pk_mul_f32 v[18:19], v[46:47], v[64:65] op_sel_hi:[1,0]
	v_cvt_pk_bf16_f32 v6, v6, v7
	v_cvt_pk_bf16_f32 v7, v8, v9
	global_store_dwordx2 v[30:31], v[6:7], off offset:128
	s_waitcnt vmcnt(10)
	v_pk_mul_f32 v[6:7], v[18:19], v[128:129]
	v_pk_mul_f32 v[8:9], v[16:17], v[130:131]
	v_cvt_pk_bf16_f32 v6, v6, v7
	v_cvt_pk_bf16_f32 v7, v8, v9
	global_store_dwordx2 v[30:31], v[6:7], off offset:144
	v_pk_mul_f32 v[16:17], v[24:25], v[64:65] op_sel_hi:[1,0]
	v_pk_mul_f32 v[18:19], v[20:21], v[64:65] op_sel_hi:[1,0]
	s_waitcnt vmcnt(10)
	v_pk_mul_f32 v[6:7], v[16:17], v[132:133]
	v_pk_mul_f32 v[8:9], v[18:19], v[134:135]
	v_cvt_pk_bf16_f32 v6, v6, v7
	v_cvt_pk_bf16_f32 v7, v8, v9
	global_store_dwordx2 v[30:31], v[6:7], off offset:160
	global_load_dwordx4 v[6:9], v65, s[4:5] offset:352
	v_pk_mul_f32 v[16:17], v[26:27], v[64:65] op_sel_hi:[1,0]
	v_pk_mul_f32 v[18:19], v[22:23], v[64:65] op_sel_hi:[1,0]
	s_waitcnt vmcnt(0)
	v_pk_mul_f32 v[6:7], v[16:17], v[6:7]
	v_pk_mul_f32 v[8:9], v[18:19], v[8:9]
	v_cvt_pk_bf16_f32 v6, v6, v7
	v_cvt_pk_bf16_f32 v7, v8, v9
	global_store_dwordx2 v[30:31], v[6:7], off offset:176
	global_load_dwordx4 v[6:9], v65, s[4:5] offset:384
	v_pk_mul_f32 v[16:17], v[28:29], v[64:65] op_sel_hi:[1,0]
	s_waitcnt vmcnt(0)
	v_pk_mul_f32 v[2:3], v[2:3], v[8:9]
	v_pk_mul_f32 v[6:7], v[16:17], v[6:7]
	s_nop 0
	v_cvt_pk_bf16_f32 v6, v6, v7
	v_cvt_pk_bf16_f32 v7, v2, v3
	global_store_dwordx2 v[30:31], v[6:7], off offset:192
	global_load_dwordx4 v[6:9], v65, s[4:5] offset:416
	v_pk_mul_f32 v[2:3], v[86:87], v[64:65] op_sel_hi:[1,0]
	s_waitcnt vmcnt(0)
	v_pk_mul_f32 v[0:1], v[0:1], v[8:9]
	v_pk_mul_f32 v[2:3], v[2:3], v[6:7]
	v_pk_mul_f32 v[6:7], v[10:11], v[64:65] op_sel_hi:[1,0]
	v_cvt_pk_bf16_f32 v2, v2, v3
	v_cvt_pk_bf16_f32 v3, v0, v1
	global_store_dwordx2 v[30:31], v[2:3], off offset:208
	global_load_dwordx4 v[0:3], v65, s[4:5] offset:448
	s_waitcnt vmcnt(0)
	v_pk_mul_f32 v[0:1], v[6:7], v[0:1]
	v_pk_mul_f32 v[2:3], v[4:5], v[2:3]
	v_cvt_pk_bf16_f32 v0, v0, v1
	v_cvt_pk_bf16_f32 v1, v2, v3
	global_store_dwordx2 v[30:31], v[0:1], off offset:224
	global_load_dwordx4 v[0:3], v65, s[4:5] offset:480
	v_pk_mul_f32 v[4:5], v[12:13], v[64:65] op_sel_hi:[1,0]
	v_pk_mul_f32 v[6:7], v[14:15], v[64:65] op_sel_hi:[1,0]
	s_waitcnt vmcnt(0)
	v_pk_mul_f32 v[0:1], v[4:5], v[0:1]
	v_pk_mul_f32 v[2:3], v[6:7], v[2:3]
	v_cvt_pk_bf16_f32 v0, v0, v1
	v_cvt_pk_bf16_f32 v1, v2, v3
	global_store_dwordx2 v[30:31], v[0:1], off offset:240

; __device__ __forceinline__ void attn_item(PC p, int wv, int L, int item, LAS unsigned char* lds) {
;     ...
;         lam = __expf(s1) - __expf(s2) + lam_init;
;     ...
;     if (m == 0) {
;         float ssq = 0.f;
; #pragma unroll
;         for (int dvt = 0; dvt < 4; ++dvt)
; #pragma unroll
;             for (int r = 0; r < 16; ++r) { const int dv = 32 * dvt + (r >> 2) * 8 + 4 * g + (r & 3); const float o = O[dvt][r] * inv - lam * Oex[(qs * 128 + dv) * 32 + j]; O[dvt][r] = o; ssq += o * o; }
.LBB0_1042:
	s_and_b64 vcc, exec, s[6:7]
	s_waitcnt lgkmcnt(0)
	s_barrier
	s_cbranch_vccnz .LBB0_1044
	v_add_f32_e32 v65, v186, v188
	v_add_f32_e32 v66, v187, v189
	v_mul_f32_e32 v65, 0x3fb8aa3b, v65
	v_mul_f32_e32 v66, 0x3fb8aa3b, v66
	v_exp_f32_e32 v65, v65
	v_exp_f32_e32 v66, v66
	v_readlane_b32 s6, v246, 10
	v_lshlrev_b32_e32 v136, 12, v143
	s_lshl_b32 s58, s16, 1
	v_sub_f32_e32 v65, v65, v66
	v_add_f32_e32 v66, v152, v65
	v_lshl_add_u32 v65, v185, 2, s6
	v_lshl_add_u32 v67, v190, 9, v65
	v_add_u32_e32 v68, 0x400, v67
	ds_read2_b32 v[74:75], v67 offset1:32
	ds_read2_b32 v[70:71], v67 offset0:64 offset1:96
	ds_read2_b32 v[84:85], v68 offset1:32
	ds_read2_b32 v[92:93], v68 offset0:64 offset1:96
	v_add_u32_e32 v68, 0x800, v67
	ds_read2_b32 v[108:109], v68 offset1:32
	ds_read2_b32 v[110:111], v68 offset0:64 offset1:96
	v_add_u32_e32 v68, 0xc00, v67
	ds_read2_b32 v[112:113], v68 offset1:32
	ds_read2_b32 v[114:115], v68 offset0:64 offset1:96
	v_add_u32_e32 v68, 0x1000, v67
	ds_read2_b32 v[116:117], v68 offset0:32 offset1:64
	v_add_u32_e32 v68, 0x1100, v67
	ds_read2_b32 v[118:119], v68 offset0:32 offset1:192
	v_add_u32_e32 v68, 0x1400, v67
	ds_read2_b32 v[120:121], v68 offset0:32 offset1:64
	v_add_u32_e32 v68, 0x1500, v67
	ds_read2_b32 v[122:123], v68 offset0:32 offset1:192
	v_add_u32_e32 v68, 0x1800, v67
	ds_read2_b32 v[124:125], v68 offset0:32 offset1:64
	v_add_u32_e32 v68, 0x1900, v67
	ds_read2_b32 v[126:127], v68 offset0:32 offset1:192
	v_add_u32_e32 v68, 0x1c00, v67
	ds_read2_b32 v[128:129], v68 offset0:32 offset1:64
	v_add_u32_e32 v68, 0x80, v67
	ds_read2st64_b32 v[130:131], v68 offset0:29 offset1:32
	v_add_u32_e32 v68, 0x2000, v67
	v_lshl_add_u32 v65, v141, 7, v65
	ds_read2_b32 v[132:133], v68 offset0:64 offset1:96
	v_add_u32_e32 v68, 0x2400, v67
	ds_read2st64_b32 v[96:97], v65 offset0:16 offset1:32
	ds_read2_b32 v[106:107], v68 offset1:32
	ds_read2_b32 v[134:135], v68 offset0:64 offset1:96
	v_add_u32_e32 v68, 0x2800, v67
	ds_read2_b32 v[100:101], v68 offset1:32
	ds_read2_b32 v[104:105], v68 offset0:64 offset1:96
	v_add_u32_e32 v68, 0x2c00, v67
	ds_read2_b32 v[94:95], v68 offset1:32
	ds_read2_b32 v[98:99], v68 offset0:64 offset1:96
	v_add_u32_e32 v68, 0x3000, v67
	ds_read2_b32 v[90:91], v68 offset0:32 offset1:64
	v_add_u32_e32 v68, 0x3100, v67
	ds_read2_b32 v[86:87], v68 offset0:32 offset1:192
	v_add_u32_e32 v68, 0x3400, v67
	ds_read2_b32 v[88:89], v68 offset0:32 offset1:64
	v_add_u32_e32 v68, 0x3500, v67
	ds_read2_b32 v[78:79], v68 offset0:32 offset1:192
	v_add_u32_e32 v68, 0x3800, v67
	ds_read2_b32 v[80:81], v68 offset0:32 offset1:64
	v_add_u32_e32 v68, 0x3900, v67
	ds_read2_b32 v[72:73], v68 offset0:32 offset1:192
	v_add_u32_e32 v68, 0x3c00, v67
	s_load_dwordx2 s[6:7], s[56:57], 0x48
	s_load_dwordx2 s[8:9], s[56:57], 0x110
	ds_read2_b32 v[76:77], v68 offset0:32 offset1:64
	ds_read_b32 v102, v65 offset:12288
	ds_read_b32 v83, v67 offset:15744
	v_lshlrev_b32_e32 v65, 2, v141
	s_waitcnt lgkmcnt(0)
	v_pk_mul_f32 v[70:71], v[66:67], v[70:71] op_sel_hi:[0,1]
	v_pk_fma_f32 v[70:71], v[50:51], v[64:65], v[70:71] op_sel_hi:[1,0,1] neg_lo:[0,0,1] neg_hi:[0,0,1]
	v_pk_mul_f32 v[50:51], v[66:67], v[74:75] op_sel_hi:[0,1]
	v_pk_fma_f32 v[74:75], v[48:49], v[64:65], v[50:51] op_sel_hi:[1,0,1] neg_lo:[0,0,1] neg_hi:[0,0,1]
	v_mul_f32_e32 v82, v71, v71
	v_mul_f32_e32 v48, v75, v75
	v_pk_fma_f32 v[142:143], v[74:75], v[74:75], v[48:49] op_sel_hi:[1,1,0]
	v_pk_mul_f32 v[84:85], v[66:67], v[84:85] op_sel_hi:[0,1]
	v_pk_fma_f32 v[142:143], v[70:71], v[70:71], v[142:143]
	v_pk_fma_f32 v[84:85], v[52:53], v[64:65], v[84:85] op_sel_hi:[1,0,1] neg_lo:[0,0,1] neg_hi:[0,0,1]
	v_pk_add_f32 v[142:143], v[142:143], v[82:83] op_sel_hi:[1,0]
	v_pk_mul_f32 v[92:93], v[66:67], v[92:93] op_sel_hi:[0,1]
	v_pk_fma_f32 v[52:53], v[84:85], v[84:85], v[142:143]
	v_mul_f32_e32 v82, v85, v85
	v_pk_fma_f32 v[54:55], v[54:55], v[64:65], v[92:93] op_sel_hi:[1,0,1] neg_lo:[0,0,1] neg_hi:[0,0,1]
	v_pk_add_f32 v[52:53], v[52:53], v[82:83] op_sel_hi:[1,0]
	v_mul_f32_e32 v82, v55, v55
	v_pk_fma_f32 v[52:53], v[54:55], v[54:55], v[52:53]
	global_load_dwordx4 v[48:51], v65, s[6:7] offset:512
	v_pk_add_f32 v[92:93], v[52:53], v[82:83] op_sel_hi:[1,0]
	v_pk_mul_f32 v[52:53], v[66:67], v[110:111] op_sel_hi:[0,1]
	v_pk_fma_f32 v[52:53], v[58:59], v[64:65], v[52:53] op_sel_hi:[1,0,1] neg_lo:[0,0,1] neg_hi:[0,0,1]
	v_pk_mul_f32 v[58:59], v[66:67], v[108:109] op_sel_hi:[0,1]
	v_pk_fma_f32 v[58:59], v[56:57], v[64:65], v[58:59] op_sel_hi:[1,0,1] neg_lo:[0,0,1] neg_hi:[0,0,1]
	v_mov_b32_e32 v103, v90
	v_pk_fma_f32 v[56:57], v[58:59], v[58:59], v[92:93]
	v_mul_f32_e32 v82, v59, v59
	v_pk_add_f32 v[56:57], v[56:57], v[82:83] op_sel_hi:[1,0]
	v_mul_f32_e32 v82, v53, v53
	v_pk_fma_f32 v[56:57], v[52:53], v[52:53], v[56:57]
	v_lshl_add_u64 v[68:69], s[8:9], 0, v[136:137]
	v_pk_add_f32 v[92:93], v[56:57], v[82:83] op_sel_hi:[1,0]
	v_pk_mul_f32 v[56:57], v[66:67], v[114:115] op_sel_hi:[0,1]
	v_pk_fma_f32 v[56:57], v[62:63], v[64:65], v[56:57] op_sel_hi:[1,0,1] neg_lo:[0,0,1] neg_hi:[0,0,1]
	v_pk_mul_f32 v[62:63], v[66:67], v[112:113] op_sel_hi:[0,1]
	v_pk_fma_f32 v[60:61], v[60:61], v[64:65], v[62:63] op_sel_hi:[1,0,1] neg_lo:[0,0,1] neg_hi:[0,0,1]
	v_lshlrev_b32_e32 v136, 1, v141
	v_pk_fma_f32 v[62:63], v[60:61], v[60:61], v[92:93]
	v_mul_f32_e32 v82, v61, v61
	v_pk_add_f32 v[62:63], v[62:63], v[82:83] op_sel_hi:[1,0]
	v_mul_f32_e32 v82, v57, v57
	v_pk_fma_f32 v[62:63], v[56:57], v[56:57], v[62:63]
	s_nop 0
	v_pk_add_f32 v[92:93], v[62:63], v[82:83] op_sel_hi:[1,0]
	v_mov_b32_e32 v62, v117
	v_mov_b32_e32 v63, v118
	v_pk_mul_f32 v[62:63], v[66:67], v[62:63] op_sel_hi:[0,1]
; __device__ __forceinline__ void attn_item(PC p, int wv, int L, int item, LAS unsigned char* lds) {
;     ...
;     if (m == 0) {
;         float ssq = 0.f;
; #pragma unroll
;         for (int dvt = 0; dvt < 4; ++dvt)
; #pragma unroll
;             for (int r = 0; r < 16; ++r) { const int dv = 32 * dvt + (r >> 2) * 8 + 4 * g + (r & 3); const float o = O[dvt][r] * inv - lam * Oex[(qs * 128 + dv) * 32 + j]; O[dvt][r] = o; ssq += o * o; }
	v_pk_fma_f32 v[34:35], v[34:35], v[64:65], v[62:63] op_sel_hi:[1,0,1] neg_lo:[0,0,1] neg_hi:[0,0,1]
	v_mov_b32_e32 v62, v96
	v_mov_b32_e32 v63, v116
	v_pk_mul_f32 v[62:63], v[66:67], v[62:63] op_sel_hi:[0,1]
	v_pk_fma_f32 v[62:63], v[32:33], v[64:65], v[62:63] op_sel_hi:[1,0,1] neg_lo:[0,0,1] neg_hi:[0,0,1]
	s_nop 0
	v_pk_fma_f32 v[32:33], v[62:63], v[62:63], v[92:93]
	v_mul_f32_e32 v82, v63, v63
	v_pk_add_f32 v[32:33], v[32:33], v[82:83] op_sel_hi:[1,0]
	v_mul_f32_e32 v82, v35, v35
	v_pk_fma_f32 v[32:33], v[34:35], v[34:35], v[32:33]
	s_nop 0
	v_pk_add_f32 v[108:109], v[32:33], v[82:83] op_sel_hi:[1,0]
	v_mov_b32_e32 v32, v121
	v_mov_b32_e32 v33, v122
	v_pk_mul_f32 v[32:33], v[66:67], v[32:33] op_sel_hi:[0,1]
	v_pk_fma_f32 v[32:33], v[38:39], v[64:65], v[32:33] op_sel_hi:[1,0,1] neg_lo:[0,0,1] neg_hi:[0,0,1]
	v_mov_b32_e32 v38, v119
	v_mov_b32_e32 v39, v120
	v_pk_mul_f32 v[38:39], v[66:67], v[38:39] op_sel_hi:[0,1]
	v_pk_fma_f32 v[92:93], v[36:37], v[64:65], v[38:39] op_sel_hi:[1,0,1] neg_lo:[0,0,1] neg_hi:[0,0,1]
	v_mov_b32_e32 v82, v77
	v_pk_fma_f32 v[36:37], v[92:93], v[92:93], v[108:109]
	v_mul_f32_e32 v38, v93, v93
	v_pk_add_f32 v[36:37], v[36:37], v[38:39] op_sel_hi:[1,0]
	v_mul_f32_e32 v38, v33, v33
	v_pk_fma_f32 v[36:37], v[32:33], v[32:33], v[36:37]
	s_nop 0
	v_pk_add_f32 v[38:39], v[36:37], v[38:39] op_sel_hi:[1,0]
	v_mov_b32_e32 v36, v125
	v_mov_b32_e32 v37, v126
	v_pk_mul_f32 v[36:37], v[66:67], v[36:37] op_sel_hi:[0,1]
	v_pk_fma_f32 v[36:37], v[42:43], v[64:65], v[36:37] op_sel_hi:[1,0,1] neg_lo:[0,0,1] neg_hi:[0,0,1]
	v_mov_b32_e32 v42, v123
	v_mov_b32_e32 v43, v124
	v_pk_mul_f32 v[42:43], v[66:67], v[42:43] op_sel_hi:[0,1]
	v_pk_fma_f32 v[40:41], v[40:41], v[64:65], v[42:43] op_sel_hi:[1,0,1] neg_lo:[0,0,1] neg_hi:[0,0,1]
	s_nop 0
	v_pk_fma_f32 v[38:39], v[40:41], v[40:41], v[38:39]
	v_mul_f32_e32 v42, v41, v41
	v_pk_add_f32 v[38:39], v[38:39], v[42:43] op_sel_hi:[1,0]
	v_mul_f32_e32 v42, v37, v37
	v_pk_fma_f32 v[38:39], v[36:37], v[36:37], v[38:39]
	s_nop 0
	v_pk_add_f32 v[108:109], v[38:39], v[42:43] op_sel_hi:[1,0]
	v_mov_b32_e32 v42, v127
	v_mov_b32_e32 v43, v128
	v_mov_b32_e32 v38, v129
	v_mov_b32_e32 v39, v130
	v_pk_mul_f32 v[42:43], v[66:67], v[42:43] op_sel_hi:[0,1]
	v_pk_mul_f32 v[38:39], v[66:67], v[38:39] op_sel_hi:[0,1]
	v_pk_fma_f32 v[42:43], v[44:45], v[64:65], v[42:43] op_sel_hi:[1,0,1] neg_lo:[0,0,1] neg_hi:[0,0,1]
	v_pk_fma_f32 v[38:39], v[46:47], v[64:65], v[38:39] op_sel_hi:[1,0,1] neg_lo:[0,0,1] neg_hi:[0,0,1]
	v_pk_fma_f32 v[44:45], v[42:43], v[42:43], v[108:109]
	v_mul_f32_e32 v46, v43, v43
	v_pk_add_f32 v[44:45], v[44:45], v[46:47] op_sel_hi:[1,0]
	v_mul_f32_e32 v46, v39, v39
	v_pk_fma_f32 v[44:45], v[38:39], v[38:39], v[44:45]
	v_mov_b32_e32 v130, v97
	v_pk_add_f32 v[46:47], v[44:45], v[46:47] op_sel_hi:[1,0]
	v_pk_mul_f32 v[44:45], v[66:67], v[132:133] op_sel_hi:[0,1]
	v_pk_fma_f32 v[18:19], v[18:19], v[64:65], v[44:45] op_sel_hi:[1,0,1] neg_lo:[0,0,1] neg_hi:[0,0,1]
	v_pk_mul_f32 v[44:45], v[66:67], v[130:131] op_sel_hi:[0,1]
	v_pk_fma_f32 v[44:45], v[16:17], v[64:65], v[44:45] op_sel_hi:[1,0,1] neg_lo:[0,0,1] neg_hi:[0,0,1]
	s_nop 0
	v_pk_fma_f32 v[16:17], v[44:45], v[44:45], v[46:47]
	v_mul_f32_e32 v46, v45, v45
	v_pk_add_f32 v[16:17], v[16:17], v[46:47] op_sel_hi:[1,0]
	v_mul_f32_e32 v46, v19, v19
	v_pk_fma_f32 v[16:17], v[18:19], v[18:19], v[16:17]
	s_nop 0
	v_pk_add_f32 v[96:97], v[16:17], v[46:47] op_sel_hi:[1,0]
	v_pk_mul_f32 v[16:17], v[66:67], v[134:135] op_sel_hi:[0,1]
	v_pk_fma_f32 v[16:17], v[22:23], v[64:65], v[16:17] op_sel_hi:[1,0,1] neg_lo:[0,0,1] neg_hi:[0,0,1]
	v_pk_mul_f32 v[22:23], v[66:67], v[106:107] op_sel_hi:[0,1]
	v_pk_fma_f32 v[46:47], v[20:21], v[64:65], v[22:23] op_sel_hi:[1,0,1] neg_lo:[0,0,1] neg_hi:[0,0,1]
	s_nop 0
	v_pk_fma_f32 v[20:21], v[46:47], v[46:47], v[96:97]
	v_mul_f32_e32 v22, v47, v47
	v_pk_add_f32 v[20:21], v[20:21], v[22:23] op_sel_hi:[1,0]
	v_mul_f32_e32 v22, v17, v17
	v_pk_fma_f32 v[20:21], v[16:17], v[16:17], v[20:21]
	s_nop 0
	v_pk_add_f32 v[22:23], v[20:21], v[22:23] op_sel_hi:[1,0]
	v_pk_mul_f32 v[20:21], v[66:67], v[104:105] op_sel_hi:[0,1]
	v_pk_fma_f32 v[20:21], v[26:27], v[64:65], v[20:21] op_sel_hi:[1,0,1] neg_lo:[0,0,1] neg_hi:[0,0,1]
	v_pk_mul_f32 v[26:27], v[66:67], v[100:101] op_sel_hi:[0,1]
	v_pk_fma_f32 v[24:25], v[24:25], v[64:65], v[26:27] op_sel_hi:[1,0,1] neg_lo:[0,0,1] neg_hi:[0,0,1]
	s_nop 0
	v_pk_fma_f32 v[22:23], v[24:25], v[24:25], v[22:23]
	v_mul_f32_e32 v26, v25, v25
	v_pk_add_f32 v[22:23], v[22:23], v[26:27] op_sel_hi:[1,0]
	v_mul_f32_e32 v26, v21, v21
	v_pk_fma_f32 v[22:23], v[20:21], v[20:21], v[22:23]
	s_nop 0
	v_pk_add_f32 v[96:97], v[22:23], v[26:27] op_sel_hi:[1,0]
	v_pk_mul_f32 v[26:27], v[66:67], v[94:95] op_sel_hi:[0,1]
	v_pk_mul_f32 v[22:23], v[66:67], v[98:99] op_sel_hi:[0,1]
	v_pk_fma_f32 v[26:27], v[28:29], v[64:65], v[26:27] op_sel_hi:[1,0,1] neg_lo:[0,0,1] neg_hi:[0,0,1]
	v_pk_fma_f32 v[22:23], v[30:31], v[64:65], v[22:23] op_sel_hi:[1,0,1] neg_lo:[0,0,1] neg_hi:[0,0,1]
	v_pk_fma_f32 v[28:29], v[26:27], v[26:27], v[96:97]
	v_mul_f32_e32 v30, v27, v27
	v_pk_add_f32 v[28:29], v[28:29], v[30:31] op_sel_hi:[1,0]
	v_mul_f32_e32 v30, v23, v23
	v_pk_fma_f32 v[28:29], v[22:23], v[22:23], v[28:29]
	s_nop 0
	v_pk_add_f32 v[30:31], v[28:29], v[30:31] op_sel_hi:[1,0]
	v_mov_b32_e32 v28, v91
	v_mov_b32_e32 v29, v86
	v_pk_mul_f32 v[28:29], v[66:67], v[28:29] op_sel_hi:[0,1]
	v_pk_fma_f32 v[2:3], v[2:3], v[64:65], v[28:29] op_sel_hi:[1,0,1] neg_lo:[0,0,1] neg_hi:[0,0,1]
	v_pk_mul_f32 v[28:29], v[66:67], v[102:103] op_sel_hi:[0,1]
	v_pk_fma_f32 v[28:29], v[0:1], v[64:65], v[28:29] op_sel_hi:[1,0,1] neg_lo:[0,0,1] neg_hi:[0,0,1]
; __device__ __forceinline__ void attn_item(PC p, int wv, int L, int item, LAS unsigned char* lds) {
;     ...
;             for (int r = 0; r < 16; ++r) { const int dv = 32 * dvt + (r >> 2) * 8 + 4 * g + (r & 3); const float o = O[dvt][r] * inv - lam * Oex[(qs * 128 + dv) * 32 + j]; O[dvt][r] = o; ssq += o * o; }
;         ssq = sum32(ssq);
;         const float sc = rsqrtf(ssq * (1.0f / 128.0f) + 1e-6f) * (1.0f - lam_init);
;         const float* sg = p->a_subln + L * 128;
;         u16* dst = p->mix + (tok0 + q0 + j) * DM + h * 128;
; #pragma unroll
;         for (int dvt = 0; dvt < 4; ++dvt)
; #pragma unroll
;             for (int r4 = 0; r4 < 4; ++r4) {
;                 const int dv = 32 * dvt + r4 * 8 + 4 * g;
;                 u32x2 o; o.x = pack2(O[dvt][4 * r4 + 0] * sc * sg[dv + 0], O[dvt][4 * r4 + 1] * sc * sg[dv + 1]);
;                 o.y = pack2(O[dvt][4 * r4 + 2] * sc * sg[dv + 2], O[dvt][4 * r4 + 3] * sc * sg[dv + 3]);
;                 *(u32x2*)(dst + dv) = o;
;             }
	s_nop 0
	v_pk_fma_f32 v[0:1], v[28:29], v[28:29], v[30:31]
	v_mul_f32_e32 v30, v29, v29
	v_pk_add_f32 v[0:1], v[0:1], v[30:31] op_sel_hi:[1,0]
	v_mul_f32_e32 v30, v3, v3
	v_pk_fma_f32 v[0:1], v[2:3], v[2:3], v[0:1]
	s_nop 0
	v_pk_add_f32 v[30:31], v[0:1], v[30:31] op_sel_hi:[1,0]
	v_mov_b32_e32 v0, v89
	v_mov_b32_e32 v1, v78
	v_pk_mul_f32 v[0:1], v[66:67], v[0:1] op_sel_hi:[0,1]
	v_pk_fma_f32 v[0:1], v[6:7], v[64:65], v[0:1] op_sel_hi:[1,0,1] neg_lo:[0,0,1] neg_hi:[0,0,1]
	v_mov_b32_e32 v6, v87
	v_mov_b32_e32 v7, v88
	v_pk_mul_f32 v[6:7], v[66:67], v[6:7] op_sel_hi:[0,1]
	v_pk_fma_f32 v[86:87], v[4:5], v[64:65], v[6:7] op_sel_hi:[1,0,1] neg_lo:[0,0,1] neg_hi:[0,0,1]
	s_nop 0
	v_pk_fma_f32 v[4:5], v[86:87], v[86:87], v[30:31]
	v_mul_f32_e32 v6, v87, v87
	v_pk_add_f32 v[4:5], v[4:5], v[6:7] op_sel_hi:[1,0]
	v_mul_f32_e32 v6, v1, v1
	v_pk_fma_f32 v[4:5], v[0:1], v[0:1], v[4:5]
	s_nop 0
	v_pk_add_f32 v[6:7], v[4:5], v[6:7] op_sel_hi:[1,0]
	v_mov_b32_e32 v4, v81
	v_mov_b32_e32 v5, v72
	v_pk_mul_f32 v[4:5], v[66:67], v[4:5] op_sel_hi:[0,1]
	v_pk_fma_f32 v[4:5], v[10:11], v[64:65], v[4:5] op_sel_hi:[1,0,1] neg_lo:[0,0,1] neg_hi:[0,0,1]
	v_mov_b32_e32 v10, v79
	v_mov_b32_e32 v11, v80
	v_pk_mul_f32 v[10:11], v[66:67], v[10:11] op_sel_hi:[0,1]
	v_pk_fma_f32 v[10:11], v[8:9], v[64:65], v[10:11] op_sel_hi:[1,0,1] neg_lo:[0,0,1] neg_hi:[0,0,1]
	s_nop 0
	v_pk_fma_f32 v[6:7], v[10:11], v[10:11], v[6:7]
	v_mul_f32_e32 v8, v11, v11
	v_pk_add_f32 v[6:7], v[6:7], v[8:9] op_sel_hi:[1,0]
	v_mul_f32_e32 v8, v5, v5
	v_pk_fma_f32 v[6:7], v[4:5], v[4:5], v[6:7]
	s_nop 0
	v_pk_add_f32 v[6:7], v[6:7], v[8:9] op_sel_hi:[1,0]
	v_pk_mul_f32 v[8:9], v[66:67], v[82:83] op_sel_hi:[0,1]
	v_pk_fma_f32 v[14:15], v[14:15], v[64:65], v[8:9] op_sel_hi:[1,0,1] neg_lo:[0,0,1] neg_hi:[0,0,1]
	v_mov_b32_e32 v8, v73
	v_mov_b32_e32 v9, v76
	v_pk_mul_f32 v[8:9], v[66:67], v[8:9] op_sel_hi:[0,1]
	v_pk_fma_f32 v[12:13], v[12:13], v[64:65], v[8:9] op_sel_hi:[1,0,1] neg_lo:[0,0,1] neg_hi:[0,0,1]
	s_nop 0
	v_pk_fma_f32 v[6:7], v[12:13], v[12:13], v[6:7]
	v_mul_f32_e32 v8, v13, v13
	v_pk_add_f32 v[6:7], v[6:7], v[8:9] op_sel_hi:[1,0]
	v_mul_f32_e32 v8, v15, v15
	v_pk_fma_f32 v[6:7], v[14:15], v[14:15], v[6:7]
	s_nop 0
	v_pk_add_f32 v[6:7], v[6:7], v[8:9] op_sel_hi:[1,0]
	s_nop 0
	v_mov_b32_e32 v7, v6
	s_nop 1
	v_permlane32_swap_b32_e32 v6, v7
	v_add_f32_e32 v6, v6, v7
	v_fmamk_f32 v6, v6, 0x3c000000, v155
	v_mul_f32_e32 v7, 0x4b800000, v6
	v_cmp_gt_f32_e32 vcc, s53, v6
	s_nop 1
	v_cndmask_b32_e32 v6, v6, v7, vcc
	v_rsq_f32_e32 v8, v6
	v_lshl_add_u64 v[6:7], v[68:69], 0, s[58:59]
	v_lshl_add_u64 v[30:31], v[6:7], 0, v[136:137]
	v_mul_f32_e32 v6, 0x45800000, v8
	v_cndmask_b32_e32 v6, v8, v6, vcc
	v_mul_f32_e32 v64, v153, v6
	v_pk_mul_f32 v[6:7], v[74:75], v[64:65] op_sel_hi:[1,0]
	v_pk_mul_f32 v[8:9], v[70:71], v[64:65] op_sel_hi:[1,0]
	s_waitcnt vmcnt(0)
	v_pk_mul_f32 v[6:7], v[48:49], v[6:7]
	v_pk_mul_f32 v[8:9], v[50:51], v[8:9]
	v_cvt_pk_bf16_f32 v6, v6, v7
	v_cvt_pk_bf16_f32 v7, v8, v9
	global_load_dwordx4 v[96:99], v65, s[6:7] offset:544
	global_load_dwordx4 v[100:103], v65, s[6:7] offset:576
	global_load_dwordx4 v[104:107], v65, s[6:7] offset:608
	global_load_dwordx4 v[108:111], v65, s[6:7] offset:640
	global_load_dwordx4 v[112:115], v65, s[6:7] offset:672
	global_load_dwordx4 v[116:119], v65, s[6:7] offset:704
	global_load_dwordx4 v[120:123], v65, s[6:7] offset:736
	global_load_dwordx4 v[124:127], v65, s[6:7] offset:768
	global_load_dwordx4 v[128:131], v65, s[6:7] offset:800
	global_load_dwordx4 v[132:135], v65, s[6:7] offset:832
	global_store_dwordx2 v[30:31], v[6:7], off
	v_pk_mul_f32 v[48:49], v[84:85], v[64:65] op_sel_hi:[1,0]
	v_pk_mul_f32 v[50:51], v[56:57], v[64:65] op_sel_hi:[1,0]
	v_pk_mul_f32 v[34:35], v[34:35], v[64:65] op_sel_hi:[1,0]
	v_pk_mul_f32 v[32:33], v[32:33], v[64:65] op_sel_hi:[1,0]
	v_pk_mul_f32 v[18:19], v[18:19], v[64:65] op_sel_hi:[1,0]
	v_pk_mul_f32 v[16:17], v[16:17], v[64:65] op_sel_hi:[1,0]
	v_pk_mul_f32 v[2:3], v[2:3], v[64:65] op_sel_hi:[1,0]
	v_pk_mul_f32 v[0:1], v[0:1], v[64:65] op_sel_hi:[1,0]
	v_pk_mul_f32 v[4:5], v[4:5], v[64:65] op_sel_hi:[1,0]
	s_waitcnt vmcnt(10)
	v_pk_mul_f32 v[6:7], v[96:97], v[48:49]
	v_pk_mul_f32 v[48:49], v[54:55], v[64:65] op_sel_hi:[1,0]
	v_cvt_pk_bf16_f32 v6, v6, v7
	v_pk_mul_f32 v[8:9], v[98:99], v[48:49]
	v_pk_mul_f32 v[48:49], v[58:59], v[64:65] op_sel_hi:[1,0]
	v_cvt_pk_bf16_f32 v7, v8, v9
	global_store_dwordx2 v[30:31], v[6:7], off offset:16
	s_waitcnt vmcnt(10)
; __device__ __forceinline__ void attn_item(PC p, int wv, int L, int item, LAS unsigned char* lds) {
;     ...
; #pragma unroll
;         for (int dvt = 0; dvt < 4; ++dvt)
; #pragma unroll
;             for (int r4 = 0; r4 < 4; ++r4) {
;                 const int dv = 32 * dvt + r4 * 8 + 4 * g;
;                 u32x2 o; o.x = pack2(O[dvt][4 * r4 + 0] * sc * sg[dv + 0], O[dvt][4 * r4 + 1] * sc * sg[dv + 1]);
;                 o.y = pack2(O[dvt][4 * r4 + 2] * sc * sg[dv + 2], O[dvt][4 * r4 + 3] * sc * sg[dv + 3]);
;                 *(u32x2*)(dst + dv) = o;
;             }
	v_pk_mul_f32 v[6:7], v[48:49], v[100:101]
	v_pk_mul_f32 v[48:49], v[52:53], v[64:65] op_sel_hi:[1,0]
	v_cvt_pk_bf16_f32 v6, v6, v7
	v_pk_mul_f32 v[8:9], v[48:49], v[102:103]
	v_pk_mul_f32 v[48:49], v[60:61], v[64:65] op_sel_hi:[1,0]
	v_cvt_pk_bf16_f32 v7, v8, v9
	global_store_dwordx2 v[30:31], v[6:7], off offset:32
	s_waitcnt vmcnt(10)
	v_pk_mul_f32 v[6:7], v[48:49], v[104:105]
	v_pk_mul_f32 v[8:9], v[50:51], v[106:107]
	v_cvt_pk_bf16_f32 v6, v6, v7
	v_cvt_pk_bf16_f32 v7, v8, v9
	global_store_dwordx2 v[30:31], v[6:7], off offset:48
	v_pk_mul_f32 v[48:49], v[62:63], v[64:65] op_sel_hi:[1,0]
	s_waitcnt vmcnt(10)
	v_pk_mul_f32 v[8:9], v[34:35], v[110:111]
	v_pk_mul_f32 v[6:7], v[48:49], v[108:109]
	v_pk_mul_f32 v[34:35], v[92:93], v[64:65] op_sel_hi:[1,0]
	v_cvt_pk_bf16_f32 v6, v6, v7
	v_cvt_pk_bf16_f32 v7, v8, v9
	global_store_dwordx2 v[30:31], v[6:7], off offset:64
	s_waitcnt vmcnt(10)
	v_pk_mul_f32 v[6:7], v[34:35], v[112:113]
	v_pk_mul_f32 v[8:9], v[32:33], v[114:115]
	v_cvt_pk_bf16_f32 v6, v6, v7
	v_cvt_pk_bf16_f32 v7, v8, v9
	global_store_dwordx2 v[30:31], v[6:7], off offset:80
	v_pk_mul_f32 v[32:33], v[40:41], v[64:65] op_sel_hi:[1,0]
	v_pk_mul_f32 v[34:35], v[36:37], v[64:65] op_sel_hi:[1,0]
	s_waitcnt vmcnt(10)
	v_pk_mul_f32 v[6:7], v[32:33], v[116:117]
	v_pk_mul_f32 v[8:9], v[34:35], v[118:119]
	v_cvt_pk_bf16_f32 v6, v6, v7
	v_cvt_pk_bf16_f32 v7, v8, v9
	global_store_dwordx2 v[30:31], v[6:7], off offset:96
	v_pk_mul_f32 v[32:33], v[42:43], v[64:65] op_sel_hi:[1,0]
	v_pk_mul_f32 v[34:35], v[38:39], v[64:65] op_sel_hi:[1,0]
	s_waitcnt vmcnt(10)
	v_pk_mul_f32 v[6:7], v[32:33], v[120:121]
	v_pk_mul_f32 v[8:9], v[34:35], v[122:123]
	v_cvt_pk_bf16_f32 v6, v6, v7
	v_cvt_pk_bf16_f32 v7, v8, v9
	global_store_dwordx2 v[30:31], v[6:7], off offset:112
	v_pk_mul_f32 v[32:33], v[44:45], v[64:65] op_sel_hi:[1,0]
	s_waitcnt vmcnt(10)
	v_pk_mul_f32 v[8:9], v[18:19], v[126:127]
	v_pk_mul_f32 v[6:7], v[32:33], v[124:125]
	v_pk_mul_f32 v[18:19], v[46:47], v[64:65] op_sel_hi:[1,0]
	v_cvt_pk_bf16_f32 v6, v6, v7
	v_cvt_pk_bf16_f32 v7, v8, v9
	global_store_dwordx2 v[30:31], v[6:7], off offset:128
	s_waitcnt vmcnt(10)
	v_pk_mul_f32 v[6:7], v[18:19], v[128:129]
	v_pk_mul_f32 v[8:9], v[16:17], v[130:131]
	v_cvt_pk_bf16_f32 v6, v6, v7
	v_cvt_pk_bf16_f32 v7, v8, v9
	global_store_dwordx2 v[30:31], v[6:7], off offset:144
	v_pk_mul_f32 v[16:17], v[24:25], v[64:65] op_sel_hi:[1,0]
	v_pk_mul_f32 v[18:19], v[20:21], v[64:65] op_sel_hi:[1,0]
	s_waitcnt vmcnt(10)
	v_pk_mul_f32 v[6:7], v[16:17], v[132:133]
	v_pk_mul_f32 v[8:9], v[18:19], v[134:135]
	v_cvt_pk_bf16_f32 v6, v6, v7
	v_cvt_pk_bf16_f32 v7, v8, v9
	global_store_dwordx2 v[30:31], v[6:7], off offset:160
	global_load_dwordx4 v[6:9], v65, s[6:7] offset:864
	v_pk_mul_f32 v[16:17], v[26:27], v[64:65] op_sel_hi:[1,0]
	v_pk_mul_f32 v[18:19], v[22:23], v[64:65] op_sel_hi:[1,0]
	s_waitcnt vmcnt(0)
	v_pk_mul_f32 v[6:7], v[16:17], v[6:7]
	v_pk_mul_f32 v[8:9], v[18:19], v[8:9]
	v_cvt_pk_bf16_f32 v6, v6, v7
	v_cvt_pk_bf16_f32 v7, v8, v9
	global_store_dwordx2 v[30:31], v[6:7], off offset:176
	global_load_dwordx4 v[6:9], v65, s[6:7] offset:896
	v_pk_mul_f32 v[16:17], v[28:29], v[64:65] op_sel_hi:[1,0]
	s_waitcnt vmcnt(0)
	v_pk_mul_f32 v[2:3], v[2:3], v[8:9]
	v_pk_mul_f32 v[6:7], v[16:17], v[6:7]
	s_nop 0
	v_cvt_pk_bf16_f32 v6, v6, v7
	v_cvt_pk_bf16_f32 v7, v2, v3
	global_store_dwordx2 v[30:31], v[6:7], off offset:192
	global_load_dwordx4 v[6:9], v65, s[6:7] offset:928
	v_pk_mul_f32 v[2:3], v[86:87], v[64:65] op_sel_hi:[1,0]
	s_waitcnt vmcnt(0)
	v_pk_mul_f32 v[0:1], v[0:1], v[8:9]
	v_pk_mul_f32 v[2:3], v[2:3], v[6:7]
	v_pk_mul_f32 v[6:7], v[10:11], v[64:65] op_sel_hi:[1,0]
	v_cvt_pk_bf16_f32 v2, v2, v3
	v_cvt_pk_bf16_f32 v3, v0, v1
	global_store_dwordx2 v[30:31], v[2:3], off offset:208
	global_load_dwordx4 v[0:3], v65, s[6:7] offset:960
	s_waitcnt vmcnt(0)
	v_pk_mul_f32 v[0:1], v[6:7], v[0:1]
	v_pk_mul_f32 v[2:3], v[4:5], v[2:3]
	v_cvt_pk_bf16_f32 v0, v0, v1
	v_cvt_pk_bf16_f32 v1, v2, v3
	global_store_dwordx2 v[30:31], v[0:1], off offset:224
	global_load_dwordx4 v[0:3], v65, s[6:7] offset:992
	v_pk_mul_f32 v[4:5], v[12:13], v[64:65] op_sel_hi:[1,0]
	v_pk_mul_f32 v[6:7], v[14:15], v[64:65] op_sel_hi:[1,0]
	s_waitcnt vmcnt(0)
	v_pk_mul_f32 v[0:1], v[4:5], v[0:1]
	v_pk_mul_f32 v[2:3], v[6:7], v[2:3]
	v_cvt_pk_bf16_f32 v0, v0, v1
	v_cvt_pk_bf16_f32 v1, v2, v3
	global_store_dwordx2 v[30:31], v[0:1], off offset:240
